# m1,m2,m6,m8,m9a + m9b: W_b epilogue gate/M1 loads in two batches of 16 in flight (was 32 serialized rounds)
# speedup vs baseline: 1.0048x; 1.0048x over previous
;     __device__ __forceinline__ void operator()(const pg8::f32x4 (&acc)[2][2][4][2], const pg8::Unit& u, int wr, int wc, int fr, int fq) const {
;     ...
;         for (int ai = 0; ai < 2; ++ai)
; #pragma unroll
;             for (int m = 0; m < 4; ++m) {
;                 const int row = u.pm * 256 + ai * 128 + wr * 64 + m * 16 + fr;
; #pragma unroll
;                 for (int bj = 0; bj < 2; ++bj) {
;                     const int col = u.pn * 256 + bj * 128 + wc * 32 + 8 * fq;
;                     f(w, row, col, acc[ai][bj][m][0], acc[ai][bj][m][1]);
;                 }
.LBB0_351:
	v_mov_b32_e32 v138, v222
	s_lshl_b32 s2, s22, 8
	v_readfirstlane_b32 s1, v138
	s_ashr_i32 s15, s1, 2
	s_lshr_b32 s1, s1, 1
	s_andn2_b32 s15, s15, 63
	v_and_or_b32 v139, v138, 15, s2
	s_lshl_b32 s0, s0, 8
	s_and_b32 s1, s1, 0x60
	s_mov_b64 s[28:29], s[8:9]
	v_add_u32_e32 v140, s15, v139
	s_or_b32 s0, s1, s0
	v_lshrrev_b32_e32 v138, 1, v138
	v_and_or_b32 v138, v138, 24, s0
	s_add_u32 s22, s28, 0x16a00000
	v_ashrrev_i32_e32 v141, 31, v140
	s_addc_u32 s23, s29, 0
	v_lshlrev_b64 v[144:145], 11, v[140:141]
	v_ashrrev_i32_e32 v139, 31, v138
	s_add_u32 s28, s28, 0x8a00000
	v_lshl_add_u64 v[146:147], s[22:23], 0, v[144:145]
	v_lshlrev_b64 v[138:139], 1, v[138:139]
	s_addc_u32 s29, s29, 0
	v_lshl_add_u64 v[150:151], v[146:147], 0, v[138:139]
	v_lshl_add_u64 v[148:149], s[28:29], 0, v[144:145]
	v_lshl_add_u64 v[148:149], v[148:149], 0, v[138:139]
	v_mov_b64_e32 v[132:133], v[150:151]
	v_mov_b64_e32 v[134:135], v[148:149]
	global_load_dwordx4 v[164:167], v[132:133], off
	global_load_dwordx4 v[168:171], v[134:135], off
	global_load_dwordx4 v[172:175], v[132:133], off offset:256
	global_load_dwordx4 v[176:179], v[134:135], off offset:256
	s_mov_b64 s[98:99], 0x8000
	v_lshl_add_u64 v[136:137], v[132:133], 0, s[98:99]
	v_lshl_add_u64 v[142:143], v[134:135], 0, s[98:99]
	global_load_dwordx4 v[180:183], v[136:137], off
	global_load_dwordx4 v[184:187], v[142:143], off
	global_load_dwordx4 v[188:191], v[136:137], off offset:256
	global_load_dwordx4 v[194:197], v[142:143], off offset:256
	s_mov_b64 s[98:99], 0x10000
	v_lshl_add_u64 v[136:137], v[132:133], 0, s[98:99]
	v_lshl_add_u64 v[142:143], v[134:135], 0, s[98:99]
	global_load_dwordx4 v[202:205], v[136:137], off
	global_load_dwordx4 v[212:215], v[142:143], off
	global_load_dwordx4 v[216:219], v[136:137], off offset:256
	global_load_dwordx4 v[232:235], v[142:143], off offset:256
	s_mov_b64 s[98:99], 0x18000
	v_lshl_add_u64 v[136:137], v[132:133], 0, s[98:99]
	v_lshl_add_u64 v[142:143], v[134:135], 0, s[98:99]
	global_load_dwordx4 v[236:239], v[136:137], off
	global_load_dwordx4 v[240:243], v[142:143], off
	global_load_dwordx4 v[244:247], v[136:137], off offset:256
	global_load_dwordx4 v[128:131], v[142:143], off offset:256
	s_andn2_b64 vcc, exec, s[6:7]
	s_waitcnt vmcnt(15)
	v_lshlrev_b32_e32 v152, 16, v164
	v_and_b32_e32 v153, 0xffff0000, v164
	v_lshlrev_b32_e32 v154, 16, v165
	v_and_b32_e32 v155, 0xffff0000, v165
	v_lshlrev_b32_e32 v156, 16, v166
	v_and_b32_e32 v157, 0xffff0000, v166
	v_lshlrev_b32_e32 v158, 16, v167
	v_and_b32_e32 v159, 0xffff0000, v167
	s_waitcnt vmcnt(14)
	v_lshlrev_b32_e32 v160, 16, v168
	v_and_b32_e32 v161, 0xffff0000, v168
	v_lshlrev_b32_e32 v144, 16, v169
	v_and_b32_e32 v145, 0xffff0000, v169
	v_lshlrev_b32_e32 v162, 16, v170
	v_and_b32_e32 v163, 0xffff0000, v170
	v_lshlrev_b32_e32 v146, 16, v171
	v_and_b32_e32 v147, 0xffff0000, v171
	v_pk_fma_f32 v[126:127], v[126:127], v[154:155], v[144:145]
	v_pk_fma_f32 v[124:125], v[124:125], v[152:153], v[160:161]
	v_pk_fma_f32 v[144:145], v[122:123], v[158:159], v[146:147]
	v_pk_fma_f32 v[122:123], v[120:121], v[156:157], v[162:163]
	v_cvt_pk_bf16_f32 v120, v124, v125
	v_cvt_pk_bf16_f32 v121, v126, v127
	v_cvt_pk_bf16_f32 v122, v122, v123
	v_cvt_pk_bf16_f32 v123, v144, v145
	global_store_dwordx4 v[148:149], v[120:123], off
	s_waitcnt vmcnt(14)
	v_lshlrev_b32_e32 v124, 16, v172
	v_and_b32_e32 v125, 0xffff0000, v172
	v_lshlrev_b32_e32 v126, 16, v173
	v_and_b32_e32 v127, 0xffff0000, v173
	v_lshlrev_b32_e32 v144, 16, v174
	v_and_b32_e32 v145, 0xffff0000, v174
	v_lshlrev_b32_e32 v146, 16, v175
	v_and_b32_e32 v147, 0xffff0000, v175
	s_waitcnt vmcnt(13)
	v_lshlrev_b32_e32 v150, 16, v176
	v_and_b32_e32 v151, 0xffff0000, v176
	v_lshlrev_b32_e32 v120, 16, v177
	v_and_b32_e32 v121, 0xffff0000, v177
	v_lshlrev_b32_e32 v152, 16, v178
	v_and_b32_e32 v153, 0xffff0000, v178
	v_lshlrev_b32_e32 v122, 16, v179
	v_and_b32_e32 v123, 0xffff0000, v179
	v_pk_fma_f32 v[118:119], v[118:119], v[126:127], v[120:121]
	v_pk_fma_f32 v[116:117], v[116:117], v[124:125], v[150:151]
	v_pk_fma_f32 v[120:121], v[114:115], v[146:147], v[122:123]
	v_pk_fma_f32 v[114:115], v[112:113], v[144:145], v[152:153]
	v_cvt_pk_bf16_f32 v112, v116, v117
	v_cvt_pk_bf16_f32 v113, v118, v119
	v_cvt_pk_bf16_f32 v114, v114, v115
	v_cvt_pk_bf16_f32 v115, v120, v121
	global_store_dwordx4 v[148:149], v[112:115], off offset:256
	s_nop 1
	s_nop 1
	v_or_b32_e32 v112, 16, v140
	v_ashrrev_i32_e32 v113, 31, v112
	v_lshlrev_b64 v[112:113], 11, v[112:113]
	v_lshl_add_u64 v[114:115], s[22:23], 0, v[112:113]
	v_lshl_add_u64 v[118:119], v[114:115], 0, v[138:139]
	v_lshl_add_u64 v[116:117], s[28:29], 0, v[112:113]
	v_lshl_add_u64 v[116:117], v[116:117], 0, v[138:139]
	s_waitcnt vmcnt(13)
	v_lshlrev_b32_e32 v120, 16, v180
	v_and_b32_e32 v121, 0xffff0000, v180
	v_lshlrev_b32_e32 v122, 16, v181
	v_and_b32_e32 v123, 0xffff0000, v181
	v_lshlrev_b32_e32 v124, 16, v182
	v_and_b32_e32 v125, 0xffff0000, v182
	v_lshlrev_b32_e32 v126, 16, v183
	v_and_b32_e32 v127, 0xffff0000, v183
	s_waitcnt vmcnt(12)
	v_lshlrev_b32_e32 v144, 16, v184
	v_and_b32_e32 v145, 0xffff0000, v184
	v_lshlrev_b32_e32 v112, 16, v185
	v_and_b32_e32 v113, 0xffff0000, v185
	v_lshlrev_b32_e32 v146, 16, v186
	v_and_b32_e32 v147, 0xffff0000, v186
	v_lshlrev_b32_e32 v114, 16, v187
	v_and_b32_e32 v115, 0xffff0000, v187
	v_pk_fma_f32 v[110:111], v[110:111], v[122:123], v[112:113]
	v_pk_fma_f32 v[108:109], v[108:109], v[120:121], v[144:145]
	v_pk_fma_f32 v[112:113], v[106:107], v[126:127], v[114:115]
	v_pk_fma_f32 v[106:107], v[104:105], v[124:125], v[146:147]
	v_cvt_pk_bf16_f32 v104, v108, v109
	v_cvt_pk_bf16_f32 v105, v110, v111
	v_cvt_pk_bf16_f32 v106, v106, v107
	v_cvt_pk_bf16_f32 v107, v112, v113
	global_store_dwordx4 v[116:117], v[104:107], off
	s_waitcnt vmcnt(12)
;     __device__ __forceinline__ void operator()(const pg8::f32x4 (&acc)[2][2][4][2], const pg8::Unit& u, int wr, int wc, int fr, int fq) const {
;     ...
;         for (int ai = 0; ai < 2; ++ai)
; #pragma unroll
;             for (int m = 0; m < 4; ++m) {
;                 const int row = u.pm * 256 + ai * 128 + wr * 64 + m * 16 + fr;
; #pragma unroll
;                 for (int bj = 0; bj < 2; ++bj) {
;                     const int col = u.pn * 256 + bj * 128 + wc * 32 + 8 * fq;
;                     f(w, row, col, acc[ai][bj][m][0], acc[ai][bj][m][1]);
;                 }
	v_lshlrev_b32_e32 v108, 16, v188
	v_and_b32_e32 v109, 0xffff0000, v188
	v_lshlrev_b32_e32 v110, 16, v189
	v_and_b32_e32 v111, 0xffff0000, v189
	v_lshlrev_b32_e32 v112, 16, v190
	v_and_b32_e32 v113, 0xffff0000, v190
	v_lshlrev_b32_e32 v114, 16, v191
	v_and_b32_e32 v115, 0xffff0000, v191
	s_waitcnt vmcnt(11)
	v_lshlrev_b32_e32 v118, 16, v194
	v_and_b32_e32 v119, 0xffff0000, v194
	v_lshlrev_b32_e32 v104, 16, v195
	v_and_b32_e32 v105, 0xffff0000, v195
	v_lshlrev_b32_e32 v120, 16, v196
	v_and_b32_e32 v121, 0xffff0000, v196
	v_lshlrev_b32_e32 v106, 16, v197
	v_and_b32_e32 v107, 0xffff0000, v197
	v_pk_fma_f32 v[102:103], v[102:103], v[110:111], v[104:105]
	v_pk_fma_f32 v[100:101], v[100:101], v[108:109], v[118:119]
	v_pk_fma_f32 v[104:105], v[98:99], v[114:115], v[106:107]
	v_pk_fma_f32 v[98:99], v[96:97], v[112:113], v[120:121]
	v_cvt_pk_bf16_f32 v96, v100, v101
	v_cvt_pk_bf16_f32 v97, v102, v103
	v_cvt_pk_bf16_f32 v98, v98, v99
	v_cvt_pk_bf16_f32 v99, v104, v105
	global_store_dwordx4 v[116:117], v[96:99], off offset:256
	s_nop 1
	s_nop 1
	v_or_b32_e32 v96, 32, v140
	v_ashrrev_i32_e32 v97, 31, v96
	v_lshlrev_b64 v[96:97], 11, v[96:97]
	v_lshl_add_u64 v[98:99], s[22:23], 0, v[96:97]
	v_lshl_add_u64 v[98:99], v[98:99], 0, v[138:139]
	v_lshl_add_u64 v[96:97], s[28:29], 0, v[96:97]
	v_lshl_add_u64 v[96:97], v[96:97], 0, v[138:139]
	s_waitcnt vmcnt(11)
	v_lshlrev_b32_e32 v104, 16, v202
	v_and_b32_e32 v105, 0xffff0000, v202
	v_lshlrev_b32_e32 v106, 16, v203
	v_and_b32_e32 v107, 0xffff0000, v203
	v_lshlrev_b32_e32 v108, 16, v204
	v_and_b32_e32 v109, 0xffff0000, v204
	v_lshlrev_b32_e32 v110, 16, v205
	v_and_b32_e32 v111, 0xffff0000, v205
	s_waitcnt vmcnt(10)
	v_lshlrev_b32_e32 v112, 16, v212
	v_and_b32_e32 v113, 0xffff0000, v212
	v_lshlrev_b32_e32 v100, 16, v213
	v_and_b32_e32 v101, 0xffff0000, v213
	v_lshlrev_b32_e32 v114, 16, v214
	v_and_b32_e32 v115, 0xffff0000, v214
	v_lshlrev_b32_e32 v102, 16, v215
	v_and_b32_e32 v103, 0xffff0000, v215
	v_pk_fma_f32 v[94:95], v[94:95], v[106:107], v[100:101]
	v_pk_fma_f32 v[92:93], v[92:93], v[104:105], v[112:113]
	v_pk_fma_f32 v[100:101], v[90:91], v[110:111], v[102:103]
	v_pk_fma_f32 v[90:91], v[88:89], v[108:109], v[114:115]
	v_cvt_pk_bf16_f32 v88, v92, v93
	v_cvt_pk_bf16_f32 v89, v94, v95
	v_cvt_pk_bf16_f32 v90, v90, v91
	v_cvt_pk_bf16_f32 v91, v100, v101
	global_store_dwordx4 v[96:97], v[88:91], off
	s_waitcnt vmcnt(10)
	v_lshlrev_b32_e32 v92, 16, v216
	v_and_b32_e32 v93, 0xffff0000, v216
	v_lshlrev_b32_e32 v94, 16, v217
	v_and_b32_e32 v95, 0xffff0000, v217
	v_lshlrev_b32_e32 v98, 16, v218
	v_and_b32_e32 v99, 0xffff0000, v218
	v_lshlrev_b32_e32 v100, 16, v219
	v_and_b32_e32 v101, 0xffff0000, v219
	s_waitcnt vmcnt(9)
	v_lshlrev_b32_e32 v102, 16, v232
	v_and_b32_e32 v103, 0xffff0000, v232
	v_lshlrev_b32_e32 v88, 16, v233
	v_and_b32_e32 v89, 0xffff0000, v233
	v_lshlrev_b32_e32 v104, 16, v234
	v_and_b32_e32 v105, 0xffff0000, v234
	v_lshlrev_b32_e32 v90, 16, v235
	v_and_b32_e32 v91, 0xffff0000, v235
	v_pk_fma_f32 v[86:87], v[86:87], v[94:95], v[88:89]
	v_pk_fma_f32 v[84:85], v[84:85], v[92:93], v[102:103]
	v_pk_fma_f32 v[88:89], v[82:83], v[100:101], v[90:91]
	v_pk_fma_f32 v[82:83], v[80:81], v[98:99], v[104:105]
	v_cvt_pk_bf16_f32 v80, v84, v85
	v_cvt_pk_bf16_f32 v81, v86, v87
	v_cvt_pk_bf16_f32 v82, v82, v83
	v_cvt_pk_bf16_f32 v83, v88, v89
	global_store_dwordx4 v[96:97], v[80:83], off offset:256
	s_nop 1
	s_nop 1
	v_or_b32_e32 v80, 48, v140
	v_ashrrev_i32_e32 v81, 31, v80
	v_lshlrev_b64 v[80:81], 11, v[80:81]
	v_lshl_add_u64 v[82:83], s[22:23], 0, v[80:81]
	v_lshl_add_u64 v[86:87], v[82:83], 0, v[138:139]
	v_lshl_add_u64 v[84:85], s[28:29], 0, v[80:81]
	s_waitcnt vmcnt(9)
	v_lshlrev_b32_e32 v88, 16, v236
	v_and_b32_e32 v89, 0xffff0000, v236
	v_lshlrev_b32_e32 v90, 16, v237
	v_and_b32_e32 v91, 0xffff0000, v237
	v_lshl_add_u64 v[80:81], v[84:85], 0, v[138:139]
	v_lshlrev_b32_e32 v92, 16, v238
	v_and_b32_e32 v93, 0xffff0000, v238
	v_lshlrev_b32_e32 v94, 16, v239
	v_and_b32_e32 v95, 0xffff0000, v239
	s_waitcnt vmcnt(8)
	v_lshlrev_b32_e32 v96, 16, v240
	v_and_b32_e32 v97, 0xffff0000, v240
	v_lshlrev_b32_e32 v82, 16, v241
	v_and_b32_e32 v83, 0xffff0000, v241
	v_lshlrev_b32_e32 v98, 16, v242
	v_and_b32_e32 v99, 0xffff0000, v242
	v_lshlrev_b32_e32 v84, 16, v243
	v_and_b32_e32 v85, 0xffff0000, v243
	v_pk_fma_f32 v[78:79], v[78:79], v[90:91], v[82:83]
	v_pk_fma_f32 v[76:77], v[76:77], v[88:89], v[96:97]
	v_pk_fma_f32 v[82:83], v[74:75], v[94:95], v[84:85]
	v_pk_fma_f32 v[74:75], v[72:73], v[92:93], v[98:99]
	v_cvt_pk_bf16_f32 v72, v76, v77
	v_cvt_pk_bf16_f32 v73, v78, v79
	v_cvt_pk_bf16_f32 v74, v74, v75
	v_cvt_pk_bf16_f32 v75, v82, v83
	global_store_dwordx4 v[80:81], v[72:75], off
	s_waitcnt vmcnt(8)
	v_lshlrev_b32_e32 v76, 16, v244
	v_and_b32_e32 v77, 0xffff0000, v244
	v_lshlrev_b32_e32 v78, 16, v245
	v_and_b32_e32 v79, 0xffff0000, v245
	v_lshlrev_b32_e32 v82, 16, v246
	v_and_b32_e32 v83, 0xffff0000, v246
	v_lshlrev_b32_e32 v84, 16, v247
	v_and_b32_e32 v85, 0xffff0000, v247
	s_waitcnt vmcnt(7)
;     __device__ __forceinline__ void operator()(const pg8::f32x4 (&acc)[2][2][4][2], const pg8::Unit& u, int wr, int wc, int fr, int fq) const {
;     ...
;         for (int ai = 0; ai < 2; ++ai)
; #pragma unroll
;             for (int m = 0; m < 4; ++m) {
;                 const int row = u.pm * 256 + ai * 128 + wr * 64 + m * 16 + fr;
; #pragma unroll
;                 for (int bj = 0; bj < 2; ++bj) {
;                     const int col = u.pn * 256 + bj * 128 + wc * 32 + 8 * fq;
;                     f(w, row, col, acc[ai][bj][m][0], acc[ai][bj][m][1]);
;                 }
	v_lshlrev_b32_e32 v86, 16, v128
	v_and_b32_e32 v87, 0xffff0000, v128
	v_lshlrev_b32_e32 v72, 16, v129
	v_and_b32_e32 v73, 0xffff0000, v129
	v_lshlrev_b32_e32 v88, 16, v130
	v_and_b32_e32 v89, 0xffff0000, v130
	v_lshlrev_b32_e32 v74, 16, v131
	v_and_b32_e32 v75, 0xffff0000, v131
	v_pk_fma_f32 v[70:71], v[70:71], v[78:79], v[72:73]
	v_pk_fma_f32 v[68:69], v[68:69], v[76:77], v[86:87]
	v_pk_fma_f32 v[72:73], v[66:67], v[84:85], v[74:75]
	v_pk_fma_f32 v[66:67], v[64:65], v[82:83], v[88:89]
	v_cvt_pk_bf16_f32 v64, v68, v69
	v_cvt_pk_bf16_f32 v65, v70, v71
	v_cvt_pk_bf16_f32 v66, v66, v67
	v_cvt_pk_bf16_f32 v67, v72, v73
	global_store_dwordx4 v[80:81], v[64:67], off offset:256
	s_nop 1
	s_mov_b64 s[98:99], 0x40000
	v_lshl_add_u64 v[136:137], v[132:133], 0, s[98:99]
	v_lshl_add_u64 v[142:143], v[134:135], 0, s[98:99]
	global_load_dwordx4 v[164:167], v[136:137], off
	global_load_dwordx4 v[168:171], v[142:143], off
	global_load_dwordx4 v[172:175], v[136:137], off offset:256
	global_load_dwordx4 v[176:179], v[142:143], off offset:256
	s_mov_b64 s[98:99], 0x48000
	v_lshl_add_u64 v[136:137], v[132:133], 0, s[98:99]
	v_lshl_add_u64 v[142:143], v[134:135], 0, s[98:99]
	global_load_dwordx4 v[180:183], v[136:137], off
	global_load_dwordx4 v[184:187], v[142:143], off
	global_load_dwordx4 v[188:191], v[136:137], off offset:256
	global_load_dwordx4 v[194:197], v[142:143], off offset:256
	s_mov_b64 s[98:99], 0x50000
	v_lshl_add_u64 v[136:137], v[132:133], 0, s[98:99]
	v_lshl_add_u64 v[142:143], v[134:135], 0, s[98:99]
	global_load_dwordx4 v[202:205], v[136:137], off
	global_load_dwordx4 v[212:215], v[142:143], off
	global_load_dwordx4 v[216:219], v[136:137], off offset:256
	global_load_dwordx4 v[232:235], v[142:143], off offset:256
	s_mov_b64 s[98:99], 0x58000
	v_lshl_add_u64 v[136:137], v[132:133], 0, s[98:99]
	v_lshl_add_u64 v[142:143], v[134:135], 0, s[98:99]
	global_load_dwordx4 v[236:239], v[136:137], off
	global_load_dwordx4 v[240:243], v[142:143], off
	global_load_dwordx4 v[244:247], v[136:137], off offset:256
	global_load_dwordx4 v[128:131], v[142:143], off offset:256
	v_add_u32_e32 v64, 0x80, v140
	v_ashrrev_i32_e32 v65, 31, v64
	v_lshlrev_b64 v[64:65], 11, v[64:65]
	v_lshl_add_u64 v[66:67], s[22:23], 0, v[64:65]
	v_lshl_add_u64 v[70:71], v[66:67], 0, v[138:139]
	v_lshl_add_u64 v[68:69], s[28:29], 0, v[64:65]
	v_lshl_add_u64 v[68:69], v[68:69], 0, v[138:139]
	s_waitcnt vmcnt(15)
	v_lshlrev_b32_e32 v72, 16, v164
	v_and_b32_e32 v73, 0xffff0000, v164
	v_lshlrev_b32_e32 v74, 16, v165
	v_and_b32_e32 v75, 0xffff0000, v165
	v_lshlrev_b32_e32 v76, 16, v166
	v_and_b32_e32 v77, 0xffff0000, v166
	v_lshlrev_b32_e32 v78, 16, v167
	v_and_b32_e32 v79, 0xffff0000, v167
	s_waitcnt vmcnt(14)
	v_lshlrev_b32_e32 v80, 16, v168
	v_and_b32_e32 v81, 0xffff0000, v168
	v_lshlrev_b32_e32 v64, 16, v169
	v_and_b32_e32 v65, 0xffff0000, v169
	v_lshlrev_b32_e32 v82, 16, v170
	v_and_b32_e32 v83, 0xffff0000, v170
	v_lshlrev_b32_e32 v66, 16, v171
	v_and_b32_e32 v67, 0xffff0000, v171
	v_pk_fma_f32 v[62:63], v[62:63], v[74:75], v[64:65]
	v_pk_fma_f32 v[60:61], v[60:61], v[72:73], v[80:81]
	v_pk_fma_f32 v[64:65], v[58:59], v[78:79], v[66:67]
	v_pk_fma_f32 v[58:59], v[56:57], v[76:77], v[82:83]
	v_cvt_pk_bf16_f32 v56, v60, v61
	v_cvt_pk_bf16_f32 v57, v62, v63
	v_cvt_pk_bf16_f32 v58, v58, v59
	v_cvt_pk_bf16_f32 v59, v64, v65
	global_store_dwordx4 v[68:69], v[56:59], off
	s_waitcnt vmcnt(14)
	v_lshlrev_b32_e32 v60, 16, v172
	v_and_b32_e32 v61, 0xffff0000, v172
	v_lshlrev_b32_e32 v62, 16, v173
	v_and_b32_e32 v63, 0xffff0000, v173
	v_lshlrev_b32_e32 v64, 16, v174
	v_and_b32_e32 v65, 0xffff0000, v174
	v_lshlrev_b32_e32 v66, 16, v175
	v_and_b32_e32 v67, 0xffff0000, v175
	s_waitcnt vmcnt(13)
	v_lshlrev_b32_e32 v70, 16, v176
	v_and_b32_e32 v71, 0xffff0000, v176
	v_lshlrev_b32_e32 v56, 16, v177
	v_and_b32_e32 v57, 0xffff0000, v177
	v_lshlrev_b32_e32 v72, 16, v178
	v_and_b32_e32 v73, 0xffff0000, v178
	v_lshlrev_b32_e32 v58, 16, v179
	v_and_b32_e32 v59, 0xffff0000, v179
	v_pk_fma_f32 v[54:55], v[54:55], v[62:63], v[56:57]
	v_pk_fma_f32 v[52:53], v[52:53], v[60:61], v[70:71]
	v_pk_fma_f32 v[56:57], v[50:51], v[66:67], v[58:59]
	v_pk_fma_f32 v[50:51], v[48:49], v[64:65], v[72:73]
	v_cvt_pk_bf16_f32 v48, v52, v53
	v_cvt_pk_bf16_f32 v49, v54, v55
	v_cvt_pk_bf16_f32 v50, v50, v51
	v_cvt_pk_bf16_f32 v51, v56, v57
	global_store_dwordx4 v[68:69], v[48:51], off offset:256
	s_nop 1
	s_nop 1
	v_add_u32_e32 v48, 0x90, v140
	v_ashrrev_i32_e32 v49, 31, v48
	v_lshlrev_b64 v[48:49], 11, v[48:49]
	v_lshl_add_u64 v[50:51], s[22:23], 0, v[48:49]
	v_lshl_add_u64 v[54:55], v[50:51], 0, v[138:139]
	v_lshl_add_u64 v[52:53], s[28:29], 0, v[48:49]
	v_lshl_add_u64 v[52:53], v[52:53], 0, v[138:139]
	s_waitcnt vmcnt(13)
	v_lshlrev_b32_e32 v56, 16, v180
	v_and_b32_e32 v57, 0xffff0000, v180
	v_lshlrev_b32_e32 v58, 16, v181
	v_and_b32_e32 v59, 0xffff0000, v181
	v_lshlrev_b32_e32 v60, 16, v182
	v_and_b32_e32 v61, 0xffff0000, v182
	v_lshlrev_b32_e32 v62, 16, v183
	v_and_b32_e32 v63, 0xffff0000, v183
	s_waitcnt vmcnt(12)
	v_lshlrev_b32_e32 v64, 16, v184
	v_and_b32_e32 v65, 0xffff0000, v184
	v_lshlrev_b32_e32 v48, 16, v185
	v_and_b32_e32 v49, 0xffff0000, v185
	v_lshlrev_b32_e32 v66, 16, v186
	v_and_b32_e32 v67, 0xffff0000, v186
	v_lshlrev_b32_e32 v50, 16, v187
	v_and_b32_e32 v51, 0xffff0000, v187
	v_pk_fma_f32 v[46:47], v[46:47], v[58:59], v[48:49]
	v_pk_fma_f32 v[44:45], v[44:45], v[56:57], v[64:65]
	v_pk_fma_f32 v[48:49], v[42:43], v[62:63], v[50:51]
	v_pk_fma_f32 v[42:43], v[40:41], v[60:61], v[66:67]
	v_cvt_pk_bf16_f32 v40, v44, v45
	v_cvt_pk_bf16_f32 v41, v46, v47
	v_cvt_pk_bf16_f32 v42, v42, v43
	v_cvt_pk_bf16_f32 v43, v48, v49
	global_store_dwordx4 v[52:53], v[40:43], off
	s_waitcnt vmcnt(12)
;     __device__ __forceinline__ void operator()(const pg8::f32x4 (&acc)[2][2][4][2], const pg8::Unit& u, int wr, int wc, int fr, int fq) const {
;     ...
;         for (int ai = 0; ai < 2; ++ai)
; #pragma unroll
;             for (int m = 0; m < 4; ++m) {
;                 const int row = u.pm * 256 + ai * 128 + wr * 64 + m * 16 + fr;
; #pragma unroll
;                 for (int bj = 0; bj < 2; ++bj) {
;                     const int col = u.pn * 256 + bj * 128 + wc * 32 + 8 * fq;
;                     f(w, row, col, acc[ai][bj][m][0], acc[ai][bj][m][1]);
;                 }
	v_lshlrev_b32_e32 v44, 16, v188
	v_and_b32_e32 v45, 0xffff0000, v188
	v_lshlrev_b32_e32 v46, 16, v189
	v_and_b32_e32 v47, 0xffff0000, v189
	v_lshlrev_b32_e32 v48, 16, v190
	v_and_b32_e32 v49, 0xffff0000, v190
	v_lshlrev_b32_e32 v50, 16, v191
	v_and_b32_e32 v51, 0xffff0000, v191
	s_waitcnt vmcnt(11)
	v_lshlrev_b32_e32 v54, 16, v194
	v_and_b32_e32 v55, 0xffff0000, v194
	v_lshlrev_b32_e32 v40, 16, v195
	v_and_b32_e32 v41, 0xffff0000, v195
	v_lshlrev_b32_e32 v56, 16, v196
	v_and_b32_e32 v57, 0xffff0000, v196
	v_lshlrev_b32_e32 v42, 16, v197
	v_and_b32_e32 v43, 0xffff0000, v197
	v_pk_fma_f32 v[38:39], v[38:39], v[46:47], v[40:41]
	v_pk_fma_f32 v[36:37], v[36:37], v[44:45], v[54:55]
	v_pk_fma_f32 v[40:41], v[34:35], v[50:51], v[42:43]
	v_pk_fma_f32 v[34:35], v[32:33], v[48:49], v[56:57]
	v_cvt_pk_bf16_f32 v32, v36, v37
	v_cvt_pk_bf16_f32 v33, v38, v39
	v_cvt_pk_bf16_f32 v34, v34, v35
	v_cvt_pk_bf16_f32 v35, v40, v41
	global_store_dwordx4 v[52:53], v[32:35], off offset:256
	s_nop 1
	s_nop 1
	v_add_u32_e32 v32, 0xa0, v140
	v_ashrrev_i32_e32 v33, 31, v32
	v_lshlrev_b64 v[32:33], 11, v[32:33]
	v_lshl_add_u64 v[34:35], s[22:23], 0, v[32:33]
	v_lshl_add_u64 v[38:39], v[34:35], 0, v[138:139]
	v_lshl_add_u64 v[36:37], s[28:29], 0, v[32:33]
	v_lshl_add_u64 v[36:37], v[36:37], 0, v[138:139]
	s_waitcnt vmcnt(11)
	v_lshlrev_b32_e32 v40, 16, v202
	v_and_b32_e32 v41, 0xffff0000, v202
	v_lshlrev_b32_e32 v42, 16, v203
	v_and_b32_e32 v43, 0xffff0000, v203
	v_lshlrev_b32_e32 v44, 16, v204
	v_and_b32_e32 v45, 0xffff0000, v204
	v_lshlrev_b32_e32 v46, 16, v205
	v_and_b32_e32 v47, 0xffff0000, v205
	s_waitcnt vmcnt(10)
	v_lshlrev_b32_e32 v48, 16, v212
	v_and_b32_e32 v49, 0xffff0000, v212
	v_lshlrev_b32_e32 v32, 16, v213
	v_and_b32_e32 v33, 0xffff0000, v213
	v_lshlrev_b32_e32 v50, 16, v214
	v_and_b32_e32 v51, 0xffff0000, v214
	v_lshlrev_b32_e32 v34, 16, v215
	v_and_b32_e32 v35, 0xffff0000, v215
	v_pk_fma_f32 v[30:31], v[30:31], v[42:43], v[32:33]
	v_pk_fma_f32 v[28:29], v[28:29], v[40:41], v[48:49]
	v_pk_fma_f32 v[32:33], v[26:27], v[46:47], v[34:35]
	v_pk_fma_f32 v[26:27], v[24:25], v[44:45], v[50:51]
	v_cvt_pk_bf16_f32 v24, v28, v29
	v_cvt_pk_bf16_f32 v25, v30, v31
	v_cvt_pk_bf16_f32 v26, v26, v27
	v_cvt_pk_bf16_f32 v27, v32, v33
	global_store_dwordx4 v[36:37], v[24:27], off
	s_waitcnt vmcnt(10)
	v_lshlrev_b32_e32 v28, 16, v216
	v_and_b32_e32 v29, 0xffff0000, v216
	v_lshlrev_b32_e32 v30, 16, v217
	v_and_b32_e32 v31, 0xffff0000, v217
	v_lshlrev_b32_e32 v32, 16, v218
	v_and_b32_e32 v33, 0xffff0000, v218
	v_lshlrev_b32_e32 v34, 16, v219
	v_and_b32_e32 v35, 0xffff0000, v219
	s_waitcnt vmcnt(9)
	v_lshlrev_b32_e32 v38, 16, v232
	v_and_b32_e32 v39, 0xffff0000, v232
	v_lshlrev_b32_e32 v24, 16, v233
	v_and_b32_e32 v25, 0xffff0000, v233
	v_lshlrev_b32_e32 v40, 16, v234
	v_and_b32_e32 v41, 0xffff0000, v234
	v_lshlrev_b32_e32 v26, 16, v235
	v_and_b32_e32 v27, 0xffff0000, v235
	v_pk_fma_f32 v[22:23], v[22:23], v[30:31], v[24:25]
	v_pk_fma_f32 v[20:21], v[20:21], v[28:29], v[38:39]
	v_pk_fma_f32 v[24:25], v[18:19], v[34:35], v[26:27]
	v_pk_fma_f32 v[18:19], v[16:17], v[32:33], v[40:41]
	v_cvt_pk_bf16_f32 v16, v20, v21
	v_cvt_pk_bf16_f32 v17, v22, v23
	v_cvt_pk_bf16_f32 v18, v18, v19
	v_cvt_pk_bf16_f32 v19, v24, v25
	global_store_dwordx4 v[36:37], v[16:19], off offset:256
	s_nop 1
	s_nop 1
	v_add_u32_e32 v16, 0xb0, v140
	v_ashrrev_i32_e32 v17, 31, v16
	v_lshlrev_b64 v[16:17], 11, v[16:17]
	v_lshl_add_u64 v[18:19], s[22:23], 0, v[16:17]
	v_lshl_add_u64 v[22:23], v[18:19], 0, v[138:139]
	v_lshl_add_u64 v[20:21], s[28:29], 0, v[16:17]
	s_mov_b64 s[22:23], -1
	s_waitcnt vmcnt(9)
	v_lshlrev_b32_e32 v24, 16, v236
	v_and_b32_e32 v25, 0xffff0000, v236
	v_lshlrev_b32_e32 v26, 16, v237
	v_and_b32_e32 v27, 0xffff0000, v237
	v_lshl_add_u64 v[16:17], v[20:21], 0, v[138:139]
	v_lshlrev_b32_e32 v28, 16, v238
	v_and_b32_e32 v29, 0xffff0000, v238
	v_lshlrev_b32_e32 v30, 16, v239
	v_and_b32_e32 v31, 0xffff0000, v239
	s_waitcnt vmcnt(8)
	v_lshlrev_b32_e32 v32, 16, v240
	v_and_b32_e32 v33, 0xffff0000, v240
	v_lshlrev_b32_e32 v18, 16, v241
	v_and_b32_e32 v19, 0xffff0000, v241
	v_lshlrev_b32_e32 v34, 16, v242
	v_and_b32_e32 v35, 0xffff0000, v242
	v_lshlrev_b32_e32 v20, 16, v243
	v_and_b32_e32 v21, 0xffff0000, v243
	v_pk_fma_f32 v[14:15], v[14:15], v[26:27], v[18:19]
	v_pk_fma_f32 v[12:13], v[12:13], v[24:25], v[32:33]
	v_pk_fma_f32 v[18:19], v[10:11], v[30:31], v[20:21]
	v_pk_fma_f32 v[10:11], v[8:9], v[28:29], v[34:35]
	v_cvt_pk_bf16_f32 v8, v12, v13
	v_cvt_pk_bf16_f32 v9, v14, v15
	v_cvt_pk_bf16_f32 v10, v10, v11
	v_cvt_pk_bf16_f32 v11, v18, v19
	global_store_dwordx4 v[16:17], v[8:11], off
	s_waitcnt vmcnt(8)
	v_lshlrev_b32_e32 v12, 16, v244
	v_and_b32_e32 v13, 0xffff0000, v244
	v_lshlrev_b32_e32 v14, 16, v245
	v_and_b32_e32 v15, 0xffff0000, v245
	v_lshlrev_b32_e32 v18, 16, v246
	v_and_b32_e32 v19, 0xffff0000, v246
	v_lshlrev_b32_e32 v20, 16, v247
	v_and_b32_e32 v21, 0xffff0000, v247
	s_waitcnt vmcnt(7)
	v_lshlrev_b32_e32 v22, 16, v128
	v_and_b32_e32 v23, 0xffff0000, v128
	v_lshlrev_b32_e32 v8, 16, v129
	v_and_b32_e32 v9, 0xffff0000, v129
	v_lshlrev_b32_e32 v24, 16, v130
	v_and_b32_e32 v25, 0xffff0000, v130
	v_lshlrev_b32_e32 v10, 16, v131
	v_and_b32_e32 v11, 0xffff0000, v131
	v_pk_fma_f32 v[6:7], v[6:7], v[14:15], v[8:9]
	v_pk_fma_f32 v[4:5], v[4:5], v[12:13], v[22:23]
	v_pk_fma_f32 v[8:9], v[2:3], v[20:21], v[10:11]
	v_pk_fma_f32 v[2:3], v[0:1], v[18:19], v[24:25]
	v_cvt_pk_bf16_f32 v0, v4, v5
	v_cvt_pk_bf16_f32 v1, v6, v7
	v_cvt_pk_bf16_f32 v2, v2, v3
	v_cvt_pk_bf16_f32 v3, v8, v9
	global_store_dwordx4 v[16:17], v[0:3], off offset:256
	s_cbranch_vccnz .LBB0_340
	s_andn2_b64 vcc, exec, s[10:11]
	s_cbranch_vccnz .LBB0_339
	s_barrier
	s_branch .LBB0_339
